# full stack: + top-k mask select via bfe/bfi, sortable-key rewrite in indexer (hazard-audited)
# speedup vs baseline: 1.0050x; 1.0030x over previous
; DI unsigned sortable(float f) { const unsigned u = __float_as_uint(f); return (u & 0x80000000u) ? ~u : (u | 0x80000000u); }
; template <int MODE> ...
;     ...
;   for (int n = wid; n < ntile; n += 4) {
;     {
;       const int nn = n + 4 < ntile ? n + 4 : n;
; #pragma unroll
;       for (int kt = 0; kt < 4; ++kt)
; #pragma unroll
;         for (int ks = 0; ks < 2; ++ks) kn[kt][ks] = *(const bf16x8*)(kbase + (size_t)(nn * 64 + kt * 16) * PW + ks * 32);
;     }
;     unsigned base[4] = {0u, 0u, 0u, 0u};
;     u64 word[4] = {0ull, 0ull, 0ull, 0ull};
;     u64 zword[4] = {0ull, 0ull, 0ull, 0ull};
;     if (MODE == 2 && any_tie) {
; #pragma unroll
;       for (int j = 0; j < 4; ++j) base[j] = cnt[(4 * g + j) * 64 + n];
;     }
; #pragma unroll
;     for (int kt = 0; kt < 4; ++kt) {
;       f32x4 sh[4];
; #pragma unroll
;       for (int h = 0; h < 4; ++h) {
;         sh[h] = (f32x4){0.f, 0.f, 0.f, 0.f};
; #pragma unroll
;         for (int ks = 0; ks < 2; ++ks) sh[h] = MFMA16(qf[h][ks], kf[kt][ks], sh[h]);
;       }
; #pragma unroll
;       for (int j = 0; j < 4; ++j) {
;         float sc = w[j][0] * fmaxf(sh[0][j], 0.f) + w[j][1] * fmaxf(sh[1][j], 0.f) + w[j][2] * fmaxf(sh[2][j], 0.f) + w[j][3] * fmaxf(sh[3][j], 0.f);
;         sc += 0.0f;
;         const unsigned u = sortable(sc);
;         if (MODE == 4) {
;           const unsigned um = u & himask;
;           const bool eq = um == pfx[j], zr = u == 0x80000000u;
;           unsigned* qx = hist + (4 * g + j) * C1_HP + 512;
;           if (eq) {
;             const unsigned bin = u & bmask; atomicAdd(&hist[(4 * g + j) * C1_HP + (bin >> 1)], 1u << ((bin & 1u) * 16u));
;             if (!zr) { const unsigned idx = atomicAdd(&qx[320], 1u); if (idx < 64u) qx[256 + idx] = ((unsigned)n << 16) | ((unsigned)(kt * 16 + lr) << 10) | (u & 1023u); }
;           }
;           word[j] |= (u64)((unsigned)(__ballot(um > pfx[j]) >> (16 * g)) & 0xffffu) << (16 * kt);
;           zword[j] |= (u64)((unsigned)(__ballot(zr) >> (16 * g)) & 0xffffu) << (16 * kt);
;         } else if (MODE == 0 || MODE == 3) {
;           if (MODE == 3) base[j] += __popc((unsigned)(__ballot(u == 0x80000000u) >> (16 * g)) & 0xffffu);
;           if (((u ^ pfx[j]) & himask) == 0u) { const unsigned bin = (u >> shift) & bmask; atomicAdd(&hist[(4 * g + j) * C1_HP + (bin >> 1)], 1u << ((bin & 1u) * 16u)); }
.LBB0_831:
	s_waitcnt vmcnt(6)
	v_mov_b64_e32 v[102:103], v[38:39]
	v_mov_b64_e32 v[58:59], v[34:35]
	v_mov_b64_e32 v[100:101], v[36:37]
	v_mov_b64_e32 v[56:57], v[32:33]
	v_mov_b32_e32 v36, v146
	v_add_u32_e32 v146, 4, v36
	v_mfma_f32_16x16x32_f16 v[60:63], v[12:15], v[56:59], 0
	v_cmp_lt_i32_e32 vcc, s2, v146
	v_mfma_f32_16x16x32_f16 v[32:35], v[24:27], v[56:59], 0
	s_nop 0
	v_cndmask_b32_e32 v36, v146, v36, vcc
	v_lshlrev_b32_e32 v147, 6, v36
	v_or_b32_e32 v44, 16, v147
	v_mfma_f32_16x16x32_f16 v[40:43], v[4:7], v[56:59], 0
	v_or_b32_e32 v48, 32, v147
	v_mad_i64_i32 v[36:37], s[4:5], v147, s0, v[122:123]
	v_mfma_f32_16x16x32_f16 v[96:99], v[16:19], v[100:103], v[60:63]
	v_mad_i64_i32 v[44:45], s[4:5], v44, s0, v[122:123]
	v_mad_i64_i32 v[52:53], s[4:5], v48, s0, v[122:123]
	s_nop 0
	v_or_b32_e32 v60, 48, v147
	v_mad_i64_i32 v[60:61], s[4:5], v60, s0, v[122:123]
	v_mfma_f32_16x16x32_f16 v[88:91], v[0:3], v[100:103], v[32:35]
	s_nop 2
	global_load_dwordx4 v[32:35], v[36:37], off
	s_nop 0
	global_load_dwordx4 v[36:39], v[36:37], off offset:64
	s_nop 1
	v_mfma_f32_16x16x32_f16 v[92:95], v[8:11], v[100:103], v[40:43]
	s_nop 2
	global_load_dwordx4 v[40:43], v[44:45], off
	global_load_dwordx4 v[44:47], v[44:45], off offset:64
	global_load_dwordx4 v[48:51], v[52:53], off
	global_load_dwordx4 v[52:55], v[52:53], off offset:64
	v_mfma_f32_16x16x32_f16 v[154:157], v[20:23], v[56:59], 0
	global_load_dwordx4 v[56:59], v[60:61], off
	s_nop 0
	global_load_dwordx4 v[60:63], v[60:61], off offset:64
	v_mfma_f32_16x16x32_f16 v[100:103], v[28:31], v[100:103], v[154:157]
	s_nop 3
	v_max_f32_e32 v154, 0, v88
	v_max_f32_e32 v155, 0, v92
	v_max_f32_e32 v156, 0, v96
	v_pk_mul_f32 v[154:155], v[154:155], v[106:107]
	v_max_f32_e32 v157, 0, v100
	v_pk_mul_f32 v[156:157], v[156:157], v[108:109]
	v_add_f32_e32 v88, v154, v155
	v_add_f32_e32 v88, v88, v156
	v_add_f32_e32 v88, v88, v157
	v_add_f32_e32 v88, 0, v88
	v_ashrrev_i32_e32 v92, 31, v88
	v_or_b32_e32 v92, 0x80000000, v92
	v_xor_b32_e32 v88, v92, v88
	v_bitop3_b32 v92, v88, s30, v142 bitop3:0x48
	v_cmp_eq_u32_e64 s[4:5], 0, v92
	s_and_saveexec_b64 s[10:11], s[4:5]
	s_cbranch_execz .LBB0_833
	v_lshrrev_b32_e32 v88, s12, v88
	v_and_b32_e32 v88, s31, v88
	v_lshlrev_b32_e32 v92, 1, v88
	v_and_b32_e32 v92, -4, v92
	v_lshlrev_b32_e32 v88, 4, v88
	v_add_u32_e32 v92, v137, v92
	v_lshlrev_b32_e64 v88, v88, 1
	ds_add_u32 v92, v88
.LBB0_833:
	s_or_b64 exec, exec, s[10:11]
	v_max_f32_e32 v88, 0, v89
	v_max_f32_e32 v89, 0, v93
	v_pk_mul_f32 v[88:89], v[88:89], v[110:111]
	v_max_f32_e32 v92, 0, v97
	v_max_f32_e32 v93, 0, v101
	v_pk_mul_f32 v[92:93], v[92:93], v[112:113]
	v_add_f32_e32 v88, v88, v89
	v_add_f32_e32 v88, v88, v92
	v_add_f32_e32 v88, v88, v93
	v_add_f32_e32 v88, 0, v88
	v_ashrrev_i32_e32 v89, 31, v88
	v_or_b32_e32 v89, 0x80000000, v89
	v_xor_b32_e32 v88, v89, v88
	v_bitop3_b32 v89, v88, s30, v143 bitop3:0x48
	v_cmp_eq_u32_e64 s[4:5], 0, v89
	s_and_saveexec_b64 s[10:11], s[4:5]
	s_cbranch_execz .LBB0_835
	v_lshrrev_b32_e32 v88, s12, v88
	v_and_b32_e32 v88, s31, v88
	v_lshlrev_b32_e32 v89, 1, v88
	v_and_b32_e32 v89, -4, v89
	v_lshlrev_b32_e32 v88, 4, v88
	v_add_u32_e32 v89, v137, v89
	v_lshlrev_b32_e64 v88, v88, 1
	ds_add_u32 v89, v88 offset:4112
.LBB0_835:
	s_or_b64 exec, exec, s[10:11]
	v_max_f32_e32 v88, 0, v90
	v_max_f32_e32 v89, 0, v94
	v_max_f32_e32 v92, 0, v98
	v_max_f32_e32 v90, v102, v102
	v_pk_mul_f32 v[88:89], v[88:89], v[114:115]
	v_max_f32_e32 v93, 0, v90
	v_pk_mul_f32 v[92:93], v[92:93], v[116:117]
	v_add_f32_e32 v88, v88, v89
	v_add_f32_e32 v88, v88, v92
	v_add_f32_e32 v88, v88, v93
	v_add_f32_e32 v88, 0, v88
	v_ashrrev_i32_e32 v89, 31, v88
	v_or_b32_e32 v89, 0x80000000, v89
	v_xor_b32_e32 v88, v89, v88
	v_bitop3_b32 v89, v88, s30, v144 bitop3:0x48
	v_cmp_eq_u32_e64 s[4:5], 0, v89
	s_and_saveexec_b64 s[10:11], s[4:5]
	s_cbranch_execz .LBB0_837
	v_lshrrev_b32_e32 v88, s12, v88
	v_and_b32_e32 v88, s31, v88
	v_lshlrev_b32_e32 v89, 1, v88
	v_and_b32_e32 v89, -4, v89
	v_lshlrev_b32_e32 v88, 4, v88
	v_add_u32_e32 v89, v137, v89
	v_lshlrev_b32_e64 v88, v88, 1
	ds_add_u32 v89, v88 offset:8224
.LBB0_837:
	s_or_b64 exec, exec, s[10:11]
	v_max_f32_e32 v88, 0, v91
	v_max_f32_e32 v89, 0, v95
	v_pk_mul_f32 v[88:89], v[88:89], v[118:119]
	v_max_f32_e32 v90, 0, v99
	v_max_f32_e32 v91, 0, v103
	v_pk_mul_f32 v[90:91], v[90:91], v[120:121]
	v_add_f32_e32 v88, v88, v89
	v_add_f32_e32 v88, v88, v90
	v_add_f32_e32 v88, v88, v91
	v_add_f32_e32 v88, 0, v88
	v_ashrrev_i32_e32 v89, 31, v88
	v_or_b32_e32 v89, 0x80000000, v89
	v_xor_b32_e32 v88, v89, v88
	v_bitop3_b32 v89, v88, s30, v145 bitop3:0x48
	v_cmp_eq_u32_e64 s[4:5], 0, v89
	s_and_saveexec_b64 s[10:11], s[4:5]
	s_cbranch_execz .LBB0_839
	v_lshrrev_b32_e32 v88, s12, v88
	v_and_b32_e32 v88, s31, v88
	v_lshlrev_b32_e32 v89, 1, v88
	v_and_b32_e32 v89, -4, v89
	v_lshlrev_b32_e32 v88, 4, v88
	v_add_u32_e32 v89, v137, v89
	v_lshlrev_b32_e64 v88, v88, 1
	ds_add_u32 v89, v88 offset:12336
.LBB0_839:
	s_or_b64 exec, exec, s[10:11]
	s_waitcnt vmcnt(13)
	v_mfma_f32_16x16x32_f16 v[88:91], v[24:27], v[80:83], 0
	s_waitcnt vmcnt(12)
	v_mfma_f32_16x16x32_f16 v[92:95], v[0:3], v[84:87], v[88:91]
	v_mfma_f32_16x16x32_f16 v[88:91], v[4:7], v[80:83], 0
	v_mfma_f32_16x16x32_f16 v[96:99], v[8:11], v[84:87], v[88:91]
	v_mfma_f32_16x16x32_f16 v[88:91], v[12:15], v[80:83], 0
	v_mfma_f32_16x16x32_f16 v[80:83], v[20:23], v[80:83], 0
	v_mfma_f32_16x16x32_f16 v[88:91], v[16:19], v[84:87], v[88:91]
	v_mfma_f32_16x16x32_f16 v[80:83], v[28:31], v[84:87], v[80:83]
	s_nop 1
	v_max_f32_e32 v84, v92, v92
	s_nop 0
	v_max_f32_e32 v84, 0, v84
	v_max_f32_e32 v85, 0, v96
	v_pk_mul_f32 v[84:85], v[84:85], v[106:107]
	v_max_f32_e32 v86, 0, v88
	v_max_f32_e32 v87, 0, v80
	v_pk_mul_f32 v[86:87], v[86:87], v[108:109]
	v_add_f32_e32 v80, v84, v85
	v_add_f32_e32 v80, v80, v86
	v_add_f32_e32 v80, v80, v87
	v_add_f32_e32 v80, 0, v80
	v_ashrrev_i32_e32 v84, 31, v80
	v_or_b32_e32 v84, 0x80000000, v84
	v_xor_b32_e32 v80, v84, v80
	v_bitop3_b32 v84, v80, s30, v142 bitop3:0x48
	v_cmp_eq_u32_e64 s[4:5], 0, v84
	s_and_saveexec_b64 s[10:11], s[4:5]
	s_cbranch_execz .LBB0_841
	v_lshrrev_b32_e32 v80, s12, v80
	v_and_b32_e32 v80, s31, v80
	v_lshlrev_b32_e32 v84, 1, v80
	v_and_b32_e32 v84, -4, v84
	v_lshlrev_b32_e32 v80, 4, v80
	v_add_u32_e32 v84, v137, v84
	v_lshlrev_b32_e64 v80, v80, 1
	ds_add_u32 v84, v80
; #define MFMA16(a, b, c) __builtin_amdgcn_mfma_f32_16x16x32_f16((a), (b), (c), 0, 0, 0)
; DI unsigned sortable(float f) { const unsigned u = __float_as_uint(f); return (u & 0x80000000u) ? ~u : (u | 0x80000000u); }
; template <int MODE> ...
;     ...
; #pragma unroll
;     for (int kt = 0; kt < 4; ++kt) {
;       f32x4 sh[4];
; #pragma unroll
;       for (int h = 0; h < 4; ++h) {
;         sh[h] = (f32x4){0.f, 0.f, 0.f, 0.f};
; #pragma unroll
;         for (int ks = 0; ks < 2; ++ks) sh[h] = MFMA16(qf[h][ks], kf[kt][ks], sh[h]);
;       }
; #pragma unroll
;       for (int j = 0; j < 4; ++j) {
;         float sc = w[j][0] * fmaxf(sh[0][j], 0.f) + w[j][1] * fmaxf(sh[1][j], 0.f) + w[j][2] * fmaxf(sh[2][j], 0.f) + w[j][3] * fmaxf(sh[3][j], 0.f);
;         sc += 0.0f;
;         const unsigned u = sortable(sc);
;         if (MODE == 4) {
;           const unsigned um = u & himask;
;           const bool eq = um == pfx[j], zr = u == 0x80000000u;
;           unsigned* qx = hist + (4 * g + j) * C1_HP + 512;
;           if (eq) {
;             const unsigned bin = u & bmask; atomicAdd(&hist[(4 * g + j) * C1_HP + (bin >> 1)], 1u << ((bin & 1u) * 16u));
;             if (!zr) { const unsigned idx = atomicAdd(&qx[320], 1u); if (idx < 64u) qx[256 + idx] = ((unsigned)n << 16) | ((unsigned)(kt * 16 + lr) << 10) | (u & 1023u); }
;           }
;           word[j] |= (u64)((unsigned)(__ballot(um > pfx[j]) >> (16 * g)) & 0xffffu) << (16 * kt);
;           zword[j] |= (u64)((unsigned)(__ballot(zr) >> (16 * g)) & 0xffffu) << (16 * kt);
;         } else if (MODE == 0 || MODE == 3) {
;           if (MODE == 3) base[j] += __popc((unsigned)(__ballot(u == 0x80000000u) >> (16 * g)) & 0xffffu);
;           if (((u ^ pfx[j]) & himask) == 0u) { const unsigned bin = (u >> shift) & bmask; atomicAdd(&hist[(4 * g + j) * C1_HP + (bin >> 1)], 1u << ((bin & 1u) * 16u)); }
.LBB0_841:
	s_or_b64 exec, exec, s[10:11]
	v_max_f32_e32 v84, 0, v93
	v_max_f32_e32 v85, 0, v97
	v_pk_mul_f32 v[84:85], v[84:85], v[110:111]
	v_max_f32_e32 v80, 0, v89
	v_max_f32_e32 v81, 0, v81
	v_pk_mul_f32 v[80:81], v[80:81], v[112:113]
	v_add_f32_e32 v84, v84, v85
	v_add_f32_e32 v80, v84, v80
	v_add_f32_e32 v80, v80, v81
	v_add_f32_e32 v80, 0, v80
	v_ashrrev_i32_e32 v81, 31, v80
	v_or_b32_e32 v81, 0x80000000, v81
	v_xor_b32_e32 v80, v81, v80
	v_bitop3_b32 v81, v80, s30, v143 bitop3:0x48
	v_cmp_eq_u32_e64 s[4:5], 0, v81
	s_and_saveexec_b64 s[10:11], s[4:5]
	s_cbranch_execz .LBB0_843
	v_lshrrev_b32_e32 v80, s12, v80
	v_and_b32_e32 v80, s31, v80
	v_lshlrev_b32_e32 v81, 1, v80
	v_and_b32_e32 v81, -4, v81
	v_lshlrev_b32_e32 v80, 4, v80
	v_add_u32_e32 v81, v137, v81
	v_lshlrev_b32_e64 v80, v80, 1
	ds_add_u32 v81, v80 offset:4112
.LBB0_843:
	s_or_b64 exec, exec, s[10:11]
	v_max_f32_e32 v80, 0, v94
	v_max_f32_e32 v81, 0, v98
	v_pk_mul_f32 v[80:81], v[80:81], v[114:115]
	v_max_f32_e32 v84, 0, v90
	v_max_f32_e32 v85, 0, v82
	v_pk_mul_f32 v[84:85], v[84:85], v[116:117]
	v_add_f32_e32 v80, v80, v81
	v_add_f32_e32 v80, v80, v84
	v_add_f32_e32 v80, v80, v85
	v_add_f32_e32 v80, 0, v80
	v_ashrrev_i32_e32 v81, 31, v80
	v_or_b32_e32 v81, 0x80000000, v81
	v_xor_b32_e32 v80, v81, v80
	v_bitop3_b32 v81, v80, s30, v144 bitop3:0x48
	v_cmp_eq_u32_e64 s[4:5], 0, v81
	s_and_saveexec_b64 s[10:11], s[4:5]
	s_cbranch_execz .LBB0_845
	v_lshrrev_b32_e32 v80, s12, v80
	v_and_b32_e32 v80, s31, v80
	v_lshlrev_b32_e32 v81, 1, v80
	v_and_b32_e32 v81, -4, v81
	v_lshlrev_b32_e32 v80, 4, v80
	v_add_u32_e32 v81, v137, v81
	v_lshlrev_b32_e64 v80, v80, 1
	ds_add_u32 v81, v80 offset:8224
.LBB0_845:
	s_or_b64 exec, exec, s[10:11]
	v_max_f32_e32 v80, 0, v95
	v_max_f32_e32 v81, 0, v99
	v_pk_mul_f32 v[80:81], v[80:81], v[118:119]
	v_max_f32_e32 v82, 0, v91
	v_max_f32_e32 v83, 0, v83
	v_pk_mul_f32 v[82:83], v[82:83], v[120:121]
	v_add_f32_e32 v80, v80, v81
	v_add_f32_e32 v80, v80, v82
	v_add_f32_e32 v80, v80, v83
	v_add_f32_e32 v80, 0, v80
	v_ashrrev_i32_e32 v81, 31, v80
	v_or_b32_e32 v81, 0x80000000, v81
	v_xor_b32_e32 v80, v81, v80
	v_bitop3_b32 v81, v80, s30, v145 bitop3:0x48
	v_cmp_eq_u32_e64 s[4:5], 0, v81
	s_and_saveexec_b64 s[10:11], s[4:5]
	s_cbranch_execz .LBB0_847
	v_lshrrev_b32_e32 v80, s12, v80
	v_and_b32_e32 v80, s31, v80
	v_lshlrev_b32_e32 v81, 1, v80
	v_and_b32_e32 v81, -4, v81
	v_lshlrev_b32_e32 v80, 4, v80
	v_add_u32_e32 v81, v137, v81
	v_lshlrev_b32_e64 v80, v80, 1
	ds_add_u32 v81, v80 offset:12336
.LBB0_847:
	s_or_b64 exec, exec, s[10:11]
	s_waitcnt vmcnt(11)
	v_mfma_f32_16x16x32_f16 v[80:83], v[24:27], v[72:75], 0
	s_waitcnt vmcnt(10)
	v_mfma_f32_16x16x32_f16 v[84:87], v[0:3], v[76:79], v[80:83]
	v_mfma_f32_16x16x32_f16 v[80:83], v[4:7], v[72:75], 0
	v_mfma_f32_16x16x32_f16 v[88:91], v[8:11], v[76:79], v[80:83]
	v_mfma_f32_16x16x32_f16 v[80:83], v[12:15], v[72:75], 0
	v_mfma_f32_16x16x32_f16 v[72:75], v[20:23], v[72:75], 0
	v_mfma_f32_16x16x32_f16 v[80:83], v[16:19], v[76:79], v[80:83]
	v_mfma_f32_16x16x32_f16 v[72:75], v[28:31], v[76:79], v[72:75]
	s_nop 1
	v_max_f32_e32 v76, v84, v84
	s_nop 0
	v_max_f32_e32 v76, 0, v76
	v_max_f32_e32 v77, 0, v88
	v_pk_mul_f32 v[76:77], v[76:77], v[106:107]
	v_max_f32_e32 v78, 0, v80
	v_max_f32_e32 v79, 0, v72
	v_pk_mul_f32 v[78:79], v[78:79], v[108:109]
	v_add_f32_e32 v72, v76, v77
	v_add_f32_e32 v72, v72, v78
	v_add_f32_e32 v72, v72, v79
	v_add_f32_e32 v72, 0, v72
	v_ashrrev_i32_e32 v76, 31, v72
	v_or_b32_e32 v76, 0x80000000, v76
	v_xor_b32_e32 v72, v76, v72
	v_bitop3_b32 v76, v72, s30, v142 bitop3:0x48
	v_cmp_eq_u32_e64 s[4:5], 0, v76
	s_and_saveexec_b64 s[10:11], s[4:5]
	s_cbranch_execz .LBB0_849
	v_lshrrev_b32_e32 v72, s12, v72
	v_and_b32_e32 v72, s31, v72
	v_lshlrev_b32_e32 v76, 1, v72
	v_and_b32_e32 v76, -4, v76
	v_lshlrev_b32_e32 v72, 4, v72
	v_add_u32_e32 v76, v137, v76
	v_lshlrev_b32_e64 v72, v72, 1
	ds_add_u32 v76, v72
.LBB0_849:
	s_or_b64 exec, exec, s[10:11]
	v_max_f32_e32 v76, 0, v85
	v_max_f32_e32 v77, 0, v89
	v_pk_mul_f32 v[76:77], v[76:77], v[110:111]
	v_max_f32_e32 v72, 0, v81
	v_max_f32_e32 v73, 0, v73
	v_pk_mul_f32 v[72:73], v[72:73], v[112:113]
	v_add_f32_e32 v76, v76, v77
	v_add_f32_e32 v72, v76, v72
	v_add_f32_e32 v72, v72, v73
	v_add_f32_e32 v72, 0, v72
	v_ashrrev_i32_e32 v73, 31, v72
	v_or_b32_e32 v73, 0x80000000, v73
	v_xor_b32_e32 v72, v73, v72
	v_bitop3_b32 v73, v72, s30, v143 bitop3:0x48
	v_cmp_eq_u32_e64 s[4:5], 0, v73
	s_and_saveexec_b64 s[10:11], s[4:5]
	s_cbranch_execz .LBB0_851
	v_lshrrev_b32_e32 v72, s12, v72
	v_and_b32_e32 v72, s31, v72
	v_lshlrev_b32_e32 v73, 1, v72
	v_and_b32_e32 v73, -4, v73
	v_lshlrev_b32_e32 v72, 4, v72
	v_add_u32_e32 v73, v137, v73
	v_lshlrev_b32_e64 v72, v72, 1
	ds_add_u32 v73, v72 offset:4112
.LBB0_851:
	s_or_b64 exec, exec, s[10:11]
	v_max_f32_e32 v72, 0, v86
	v_max_f32_e32 v73, 0, v90
	v_pk_mul_f32 v[72:73], v[72:73], v[114:115]
	v_max_f32_e32 v76, 0, v82
	v_max_f32_e32 v77, 0, v74
	v_pk_mul_f32 v[76:77], v[76:77], v[116:117]
	v_add_f32_e32 v72, v72, v73
	v_add_f32_e32 v72, v72, v76
	v_add_f32_e32 v72, v72, v77
	v_add_f32_e32 v72, 0, v72
	v_ashrrev_i32_e32 v73, 31, v72
	v_or_b32_e32 v73, 0x80000000, v73
	v_xor_b32_e32 v72, v73, v72
	v_bitop3_b32 v73, v72, s30, v144 bitop3:0x48
	v_cmp_eq_u32_e64 s[4:5], 0, v73
	s_and_saveexec_b64 s[10:11], s[4:5]
	s_cbranch_execz .LBB0_853
	v_lshrrev_b32_e32 v72, s12, v72
	v_and_b32_e32 v72, s31, v72
	v_lshlrev_b32_e32 v73, 1, v72
	v_and_b32_e32 v73, -4, v73
	v_lshlrev_b32_e32 v72, 4, v72
	v_add_u32_e32 v73, v137, v73
	v_lshlrev_b32_e64 v72, v72, 1
	ds_add_u32 v73, v72 offset:8224
; #define MFMA16(a, b, c) __builtin_amdgcn_mfma_f32_16x16x32_f16((a), (b), (c), 0, 0, 0)
; DI unsigned sortable(float f) { const unsigned u = __float_as_uint(f); return (u & 0x80000000u) ? ~u : (u | 0x80000000u); }
; template <int MODE> ...
;     ...
; #pragma unroll
;     for (int kt = 0; kt < 4; ++kt) {
;       f32x4 sh[4];
; #pragma unroll
;       for (int h = 0; h < 4; ++h) {
;         sh[h] = (f32x4){0.f, 0.f, 0.f, 0.f};
; #pragma unroll
;         for (int ks = 0; ks < 2; ++ks) sh[h] = MFMA16(qf[h][ks], kf[kt][ks], sh[h]);
;       }
; #pragma unroll
;       for (int j = 0; j < 4; ++j) {
;         float sc = w[j][0] * fmaxf(sh[0][j], 0.f) + w[j][1] * fmaxf(sh[1][j], 0.f) + w[j][2] * fmaxf(sh[2][j], 0.f) + w[j][3] * fmaxf(sh[3][j], 0.f);
;         sc += 0.0f;
;         const unsigned u = sortable(sc);
;         if (MODE == 4) {
;           const unsigned um = u & himask;
;           const bool eq = um == pfx[j], zr = u == 0x80000000u;
;           unsigned* qx = hist + (4 * g + j) * C1_HP + 512;
;           if (eq) {
;             const unsigned bin = u & bmask; atomicAdd(&hist[(4 * g + j) * C1_HP + (bin >> 1)], 1u << ((bin & 1u) * 16u));
;             if (!zr) { const unsigned idx = atomicAdd(&qx[320], 1u); if (idx < 64u) qx[256 + idx] = ((unsigned)n << 16) | ((unsigned)(kt * 16 + lr) << 10) | (u & 1023u); }
;           }
;           word[j] |= (u64)((unsigned)(__ballot(um > pfx[j]) >> (16 * g)) & 0xffffu) << (16 * kt);
;           zword[j] |= (u64)((unsigned)(__ballot(zr) >> (16 * g)) & 0xffffu) << (16 * kt);
;         } else if (MODE == 0 || MODE == 3) {
;           if (MODE == 3) base[j] += __popc((unsigned)(__ballot(u == 0x80000000u) >> (16 * g)) & 0xffffu);
;           if (((u ^ pfx[j]) & himask) == 0u) { const unsigned bin = (u >> shift) & bmask; atomicAdd(&hist[(4 * g + j) * C1_HP + (bin >> 1)], 1u << ((bin & 1u) * 16u)); }
.LBB0_853:
	s_or_b64 exec, exec, s[10:11]
	v_max_f32_e32 v72, 0, v87
	v_max_f32_e32 v73, 0, v91
	v_pk_mul_f32 v[72:73], v[72:73], v[118:119]
	v_max_f32_e32 v74, 0, v83
	v_max_f32_e32 v75, 0, v75
	v_pk_mul_f32 v[74:75], v[74:75], v[120:121]
	v_add_f32_e32 v72, v72, v73
	v_add_f32_e32 v72, v72, v74
	v_add_f32_e32 v72, v72, v75
	v_add_f32_e32 v72, 0, v72
	v_ashrrev_i32_e32 v73, 31, v72
	v_or_b32_e32 v73, 0x80000000, v73
	v_xor_b32_e32 v72, v73, v72
	v_bitop3_b32 v73, v72, s30, v145 bitop3:0x48
	v_cmp_eq_u32_e64 s[4:5], 0, v73
	s_and_saveexec_b64 s[10:11], s[4:5]
	s_cbranch_execz .LBB0_855
	v_lshrrev_b32_e32 v72, s12, v72
	v_and_b32_e32 v72, s31, v72
	v_lshlrev_b32_e32 v73, 1, v72
	v_and_b32_e32 v73, -4, v73
	v_lshlrev_b32_e32 v72, 4, v72
	v_add_u32_e32 v73, v137, v73
	v_lshlrev_b32_e64 v72, v72, 1
	ds_add_u32 v73, v72 offset:12336
.LBB0_855:
	s_or_b64 exec, exec, s[10:11]
	s_waitcnt vmcnt(9)
	v_mfma_f32_16x16x32_f16 v[72:75], v[24:27], v[64:67], 0
	s_waitcnt vmcnt(8)
	v_mfma_f32_16x16x32_f16 v[76:79], v[0:3], v[68:71], v[72:75]
	v_mfma_f32_16x16x32_f16 v[72:75], v[4:7], v[64:67], 0
	v_mfma_f32_16x16x32_f16 v[80:83], v[8:11], v[68:71], v[72:75]
	v_mfma_f32_16x16x32_f16 v[72:75], v[12:15], v[64:67], 0
	v_mfma_f32_16x16x32_f16 v[64:67], v[20:23], v[64:67], 0
	v_mfma_f32_16x16x32_f16 v[72:75], v[16:19], v[68:71], v[72:75]
	v_mfma_f32_16x16x32_f16 v[64:67], v[28:31], v[68:71], v[64:67]
	s_nop 1
	v_max_f32_e32 v68, v76, v76
	s_nop 0
	v_max_f32_e32 v68, 0, v68
	v_max_f32_e32 v69, 0, v80
	v_pk_mul_f32 v[68:69], v[68:69], v[106:107]
	v_max_f32_e32 v70, 0, v72
	v_max_f32_e32 v71, 0, v64
	v_pk_mul_f32 v[70:71], v[70:71], v[108:109]
	v_add_f32_e32 v64, v68, v69
	v_add_f32_e32 v64, v64, v70
	v_add_f32_e32 v64, v64, v71
	v_add_f32_e32 v64, 0, v64
	v_ashrrev_i32_e32 v68, 31, v64
	v_or_b32_e32 v68, 0x80000000, v68
	v_xor_b32_e32 v64, v68, v64
	v_bitop3_b32 v68, v64, s30, v142 bitop3:0x48
	v_cmp_eq_u32_e64 s[4:5], 0, v68
	s_and_saveexec_b64 s[10:11], s[4:5]
	s_cbranch_execz .LBB0_857
	v_lshrrev_b32_e32 v64, s12, v64
	v_and_b32_e32 v64, s31, v64
	v_lshlrev_b32_e32 v68, 1, v64
	v_and_b32_e32 v68, -4, v68
	v_lshlrev_b32_e32 v64, 4, v64
	v_add_u32_e32 v68, v137, v68
	v_lshlrev_b32_e64 v64, v64, 1
	ds_add_u32 v68, v64
.LBB0_857:
	s_or_b64 exec, exec, s[10:11]
	v_max_f32_e32 v68, 0, v77
	v_max_f32_e32 v69, 0, v81
	v_pk_mul_f32 v[68:69], v[68:69], v[110:111]
	v_max_f32_e32 v64, 0, v73
	v_max_f32_e32 v65, 0, v65
	v_pk_mul_f32 v[64:65], v[64:65], v[112:113]
	v_add_f32_e32 v68, v68, v69
	v_add_f32_e32 v64, v68, v64
	v_add_f32_e32 v64, v64, v65
	v_add_f32_e32 v64, 0, v64
	v_ashrrev_i32_e32 v65, 31, v64
	v_or_b32_e32 v65, 0x80000000, v65
	v_xor_b32_e32 v64, v65, v64
	v_bitop3_b32 v65, v64, s30, v143 bitop3:0x48
	v_cmp_eq_u32_e64 s[4:5], 0, v65
	s_and_saveexec_b64 s[10:11], s[4:5]
	s_cbranch_execz .LBB0_859
	v_lshrrev_b32_e32 v64, s12, v64
	v_and_b32_e32 v64, s31, v64
	v_lshlrev_b32_e32 v65, 1, v64
	v_and_b32_e32 v65, -4, v65
	v_lshlrev_b32_e32 v64, 4, v64
	v_add_u32_e32 v65, v137, v65
	v_lshlrev_b32_e64 v64, v64, 1
	ds_add_u32 v65, v64 offset:4112
.LBB0_859:
	s_or_b64 exec, exec, s[10:11]
	v_max_f32_e32 v64, 0, v78
	v_max_f32_e32 v65, 0, v82
	v_pk_mul_f32 v[64:65], v[64:65], v[114:115]
	v_max_f32_e32 v68, 0, v74
	v_max_f32_e32 v69, 0, v66
	v_pk_mul_f32 v[68:69], v[68:69], v[116:117]
	v_add_f32_e32 v64, v64, v65
	v_add_f32_e32 v64, v64, v68
	v_add_f32_e32 v64, v64, v69
	v_add_f32_e32 v64, 0, v64
	v_ashrrev_i32_e32 v65, 31, v64
	v_or_b32_e32 v65, 0x80000000, v65
	v_xor_b32_e32 v64, v65, v64
	v_bitop3_b32 v65, v64, s30, v144 bitop3:0x48
	v_cmp_eq_u32_e64 s[4:5], 0, v65
	s_and_saveexec_b64 s[10:11], s[4:5]
	s_cbranch_execz .LBB0_861
	v_lshrrev_b32_e32 v64, s12, v64
	v_and_b32_e32 v64, s31, v64
	v_lshlrev_b32_e32 v65, 1, v64
	v_and_b32_e32 v65, -4, v65
	v_lshlrev_b32_e32 v64, 4, v64
	v_add_u32_e32 v65, v137, v65
	v_lshlrev_b32_e64 v64, v64, 1
	ds_add_u32 v65, v64 offset:8224
.LBB0_861:
	s_or_b64 exec, exec, s[10:11]
	v_max_f32_e32 v64, 0, v79
	v_max_f32_e32 v65, 0, v83
	v_pk_mul_f32 v[64:65], v[64:65], v[118:119]
	v_max_f32_e32 v66, 0, v75
	v_max_f32_e32 v67, 0, v67
	v_pk_mul_f32 v[66:67], v[66:67], v[120:121]
	v_add_f32_e32 v64, v64, v65
	v_add_f32_e32 v64, v64, v66
	v_add_f32_e32 v64, v64, v67
	v_add_f32_e32 v64, 0, v64
	v_ashrrev_i32_e32 v65, 31, v64
	v_or_b32_e32 v65, 0x80000000, v65
	v_xor_b32_e32 v64, v65, v64
	v_bitop3_b32 v65, v64, s30, v145 bitop3:0x48
	v_cmp_eq_u32_e64 s[4:5], 0, v65
	s_and_saveexec_b64 s[10:11], s[4:5]
	s_cbranch_execz .LBB0_830
	v_lshrrev_b32_e32 v64, s12, v64
	v_and_b32_e32 v64, s31, v64
	v_lshlrev_b32_e32 v65, 1, v64
	v_and_b32_e32 v65, -4, v65
	v_lshlrev_b32_e32 v64, 4, v64
	v_add_u32_e32 v65, v137, v65
	v_lshlrev_b32_e64 v64, v64, 1
	ds_add_u32 v65, v64 offset:12336
	s_branch .LBB0_830

; DI unsigned sortable(float f) { const unsigned u = __float_as_uint(f); return (u & 0x80000000u) ? ~u : (u | 0x80000000u); }
; template <int MODE> ...
;     ...
;         float sc = w[j][0] * fmaxf(sh[0][j], 0.f) + w[j][1] * fmaxf(sh[1][j], 0.f) + w[j][2] * fmaxf(sh[2][j], 0.f) + w[j][3] * fmaxf(sh[3][j], 0.f);
;         sc += 0.0f;
;         const unsigned u = sortable(sc);
;         if (MODE == 4) {
;           const unsigned um = u & himask;
;           const bool eq = um == pfx[j], zr = u == 0x80000000u;
;           unsigned* qx = hist + (4 * g + j) * C1_HP + 512;
;           if (eq) {
;             const unsigned bin = u & bmask; atomicAdd(&hist[(4 * g + j) * C1_HP + (bin >> 1)], 1u << ((bin & 1u) * 16u));
;             if (!zr) { const unsigned idx = atomicAdd(&qx[320], 1u); if (idx < 64u) qx[256 + idx] = ((unsigned)n << 16) | ((unsigned)(kt * 16 + lr) << 10) | (u & 1023u); }
;           }
;           word[j] |= (u64)((unsigned)(__ballot(um > pfx[j]) >> (16 * g)) & 0xffffu) << (16 * kt);
;           zword[j] |= (u64)((unsigned)(__ballot(zr) >> (16 * g)) & 0xffffu) << (16 * kt);
.LBB0_930:
	s_or_b64 exec, exec, s[24:25]
	v_cmp_gt_u32_e64 s[28:29], v64, v144
	v_cndmask_b32_e64 v64, 0, 1, s[20:21]
	v_cmp_ne_u32_e64 s[24:25], 0, v64
	v_max_f32_e32 v64, 0, v75
	v_max_f32_e32 v65, 0, v79
	v_pk_mul_f32 v[64:65], v[64:65], v[118:119]
	v_max_f32_e32 v66, 0, v83
	v_max_f32_e32 v67, 0, v67
	v_pk_mul_f32 v[66:67], v[66:67], v[120:121]
	v_add_f32_e32 v64, v64, v65
	v_add_f32_e32 v64, v64, v66
	v_add_f32_e32 v64, v64, v67
	v_add_f32_e32 v64, 0, v64
	v_ashrrev_i32_e32 v65, 31, v64
	v_or_b32_e32 v65, 0x80000000, v65
	v_xor_b32_e32 v65, v65, v64
	v_and_b32_e32 v64, s30, v65
	v_cmp_eq_u32_e32 vcc, v64, v145
	v_cmp_eq_u32_e64 s[22:23], s3, v65
	v_cmp_ne_u32_e64 s[20:21], s3, v65
	s_and_saveexec_b64 s[34:35], vcc
	s_cbranch_execz .LBB0_934
	v_and_b32_e32 v66, s31, v65
	v_lshlrev_b32_e32 v67, 1, v66
	v_and_b32_e32 v67, -4, v67
	v_lshlrev_b32_e32 v66, 4, v66
	v_add_u32_e32 v67, v137, v67
	v_lshlrev_b32_e64 v66, v66, 1
	ds_add_u32 v67, v66 offset:12336
	s_and_b64 exec, exec, s[20:21]
	s_cbranch_execz .LBB0_934
	ds_add_rtn_u32 v66, v137, v174 offset:15664
	s_waitcnt lgkmcnt(0)
	v_cmp_gt_u32_e32 vcc, 64, v66
	s_and_b64 exec, exec, vcc
	v_and_b32_e32 v65, 0x3ff, v65
	s_mov_b32 s20, 0xc000
	v_add3_u32 v65, v146, v65, s20
	v_lshl_add_u32 v66, v66, 2, v137
	ds_write_b32 v66, v65 offset:15408

; template <int MODE> ...
;     ...
;         } else if (MODE == 0 || MODE == 3) {
;           if (MODE == 3) base[j] += __popc((unsigned)(__ballot(u == 0x80000000u) >> (16 * g)) & 0xffffu);
;           if (((u ^ pfx[j]) & himask) == 0u) { const unsigned bin = (u >> shift) & bmask; atomicAdd(&hist[(4 * g + j) * C1_HP + (bin >> 1)], 1u << ((bin & 1u) * 16u)); }
;         } else {
;           const bool eq = u == pfx[j];
;           const unsigned fe = (unsigned)(__ballot(eq) >> (16 * g)) & 0xffffu;
;           if (MODE == 1) {
;             base[j] += __popc(fe);
;           } else {
;             const unsigned rank = base[j] + __popc(fe & ((1u << lr) - 1u));
;             const bool sel = (u > pfx[j]) || (eq && rank < need[j]);
;             base[j] += __popc(fe);
;             const unsigned fs = (unsigned)(__ballot(sel) >> (16 * g)) & 0xffffu;
;             word[j] |= (u64)fs << (16 * kt);
;           }
;         }
;       }
;     }
;     if ((MODE == 1 || MODE == 3) && lr == 0) {
; #pragma unroll
;       for (int j = 0; j < 4; ++j) cnt[(4 * g + j) * 64 + n] = (unsigned short)base[j];
;     }
;     if (MODE == 2 && lr == 0) {
; #pragma unroll
;       for (int j = 0; j < 4; ++j) mrow[(size_t)(4 * g + j) * 64 + n] = word[j];
.LBB0_1007:
	s_or_b64 exec, exec, s[16:17]
	v_and_b32_e32 v72, 0xffff, v94
	v_bcnt_u32_b32 v84, v72, 0
	v_and_b32_e32 v72, 0xffff, v96
	v_bcnt_u32_b32 v88, v72, 0
	v_and_b32_e32 v72, 0xffff, v76
	v_bcnt_u32_b32 v78, v72, 0
	v_cndmask_b32_e64 v72, 0, 1, s[14:15]
	v_cmp_ne_u32_e64 s[12:13], 0, v72
	v_max_f32_e32 v76, 0, v81
	v_max_f32_e32 v77, 0, v85
	v_pk_mul_f32 v[76:77], v[76:77], v[110:111]
	v_max_f32_e32 v72, 0, v89
	v_max_f32_e32 v73, 0, v73
	v_pk_mul_f32 v[72:73], v[72:73], v[112:113]
	v_add_f32_e32 v76, v76, v77
	v_add_f32_e32 v72, v76, v72
	v_add_f32_e32 v72, v72, v73
	v_add_f32_e32 v72, 0, v72
	v_max_f32_e32 v77, 0, v74
	v_ashrrev_i32_e32 v73, 31, v72
	v_or_b32_e32 v73, 0x80000000, v73
	v_xor_b32_e32 v72, v73, v72
	v_cmp_gt_u32_e64 s[14:15], v72, v33
	v_max_f32_e32 v74, v83, v83
	v_max_f32_e32 v75, v75, v75
	v_cndmask_b32_e64 v76, 0, 1, s[14:15]
	v_cmp_eq_u32_e64 s[14:15], v72, v33
	v_max_f32_e32 v75, 0, v75
	s_nop 0
	v_lshrrev_b64 v[72:73], v150, s[14:15]
	v_and_b32_e32 v72, v72, v105
	v_bcnt_u32_b32 v72, v72, 0
	v_add3_u32 v72, v78, v101, v72
	v_cmp_lt_u32_e64 s[16:17], v72, v37
	v_max_f32_e32 v73, v86, v86
	v_max_f32_e32 v78, 0, v74
	v_cndmask_b32_e64 v72, 0, 1, s[16:17]
	v_cndmask_b32_e64 v72, v76, v72, s[14:15]
	v_and_b32_e32 v72, 1, v72
	v_cmp_ne_u32_e64 s[14:15], 0, v72
	v_max_f32_e32 v72, 0, v82
	v_max_f32_e32 v73, 0, v73
	v_max_f32_e32 v79, 0, v87
	v_pk_mul_f32 v[72:73], v[72:73], v[114:115]
	v_max_f32_e32 v76, 0, v90
	v_pk_mul_f32 v[78:79], v[78:79], v[118:119]
	v_max_f32_e32 v74, 0, v91
	v_pk_mul_f32 v[76:77], v[76:77], v[116:117]
	v_pk_mul_f32 v[74:75], v[74:75], v[120:121]
	v_mov_b32_e32 v80, v72
	v_mov_b32_e32 v81, v78
	v_mov_b32_e32 v78, v73
	v_pk_add_f32 v[72:73], v[80:81], v[78:79]
	v_mov_b32_e32 v78, v76
	v_mov_b32_e32 v79, v74
	v_pk_add_f32 v[72:73], v[72:73], v[78:79]
	v_mov_b32_e32 v74, v77
	v_pk_add_f32 v[72:73], v[72:73], v[74:75]
	s_nop 0
	v_pk_add_f32 v[72:73], v[72:73], 0 op_sel_hi:[1,0]
	s_nop 0
	v_and_b32_e32 v75, 0x7fffffff, v73
	v_and_b32_e32 v74, 0x7fffffff, v72
	v_xor_b32_e32 v77, -1, v72
	v_pk_add_f32 v[74:75], v[74:75], 0 neg_lo:[1,1] neg_hi:[1,1]
	v_cmp_gt_i32_e64 s[16:17], 0, v72
	v_xor_b32_e32 v76, -1, v73
	s_nop 0
	v_cndmask_b32_e64 v72, v74, v77, s[16:17]
	v_cmp_gt_i32_e64 s[16:17], 0, v73
	s_nop 1
	v_cndmask_b32_e64 v73, v75, v76, s[16:17]
	v_cmp_gt_u32_e64 s[16:17], v73, v35
	v_cmp_eq_u32_e64 s[18:19], v73, v35
	s_nop 0
	v_cndmask_b32_e64 v74, 0, 1, s[16:17]
	v_cmp_gt_u32_e64 s[16:17], v72, v34
	s_nop 1
	v_cndmask_b32_e64 v75, 0, 1, s[16:17]
	v_cmp_eq_u32_e64 s[16:17], v72, v34
	s_nop 1
	v_lshrrev_b64 v[72:73], v150, s[16:17]
	v_and_b32_e32 v72, v72, v105
	v_bcnt_u32_b32 v72, v72, 0
	v_add3_u32 v72, v84, v98, v72
	v_cmp_lt_u32_e64 s[20:21], v72, v38
	s_nop 1
	v_cndmask_b32_e64 v72, 0, 1, s[20:21]
	v_cndmask_b32_e64 v72, v75, v72, s[16:17]
	v_and_b32_e32 v72, 1, v72
	v_cmp_ne_u32_e64 s[16:17], 0, v72
	v_lshrrev_b64 v[72:73], v150, s[18:19]
	v_and_b32_e32 v72, v72, v105
	v_bcnt_u32_b32 v72, v72, 0
	v_add3_u32 v72, v88, v99, v72
	v_cmp_lt_u32_e64 s[20:21], v72, v39
	s_nop 1
	v_cndmask_b32_e64 v72, 0, 1, s[20:21]
	v_cndmask_b32_e64 v72, v74, v72, s[18:19]
	v_and_b32_e32 v72, 1, v72
	v_cmp_ne_u32_e64 s[18:19], 0, v72
	s_and_saveexec_b64 s[20:21], s[40:41]
	s_cbranch_execz .LBB0_1001
	v_lshrrev_b64 v[72:73], v150, vcc
	v_lshrrev_b64 v[80:81], v150, s[52:53]
	v_lshlrev_b32_e32 v73, 16, v80
	v_and_or_b32 v80, v72, s33, v73
	v_lshrrev_b64 v[72:73], v150, s[54:55]
	v_lshrrev_b64 v[74:75], v150, s[44:45]
	v_lshrrev_b64 v[76:77], v150, s[48:49]
	v_lshlrev_b32_e32 v72, 16, v72
	v_and_or_b32 v77, v74, s33, v72
	v_lshrrev_b64 v[72:73], v150, s[56:57]
	v_lshlrev_b32_e32 v72, 16, v72
	v_and_or_b32 v74, v76, s33, v72
	v_lshrrev_b64 v[72:73], v150, s[4:5]
	v_lshrrev_b64 v[78:79], v150, s[50:51]
	v_lshlrev_b32_e32 v72, 16, v72
	v_and_or_b32 v78, v78, s33, v72
	v_lshrrev_b64 v[72:73], v150, s[58:59]
	v_and_b32_e32 v81, 0xffff, v72
	v_lshrrev_b64 v[72:73], v150, s[6:7]
	v_and_b32_e32 v76, 0xffff, v72
	v_lshrrev_b64 v[72:73], v150, s[8:9]
	v_and_b32_e32 v75, 0xffff, v72
	v_lshrrev_b64 v[72:73], v150, s[10:11]
	v_and_b32_e32 v79, 0xffff, v72
	v_lshrrev_b64 v[72:73], v150, s[18:19]
	v_lshlrev_b32_e32 v72, 16, v72
	v_or3_b32 v73, 0, v75, v72
	v_or3_b32 v72, v74, 0, 0
	v_lshrrev_b64 v[74:75], v150, s[16:17]
	v_lshlrev_b32_e32 v74, 16, v74
	v_or3_b32 v75, 0, v76, v74
	v_or3_b32 v74, v77, 0, 0
	v_lshrrev_b64 v[76:77], v150, s[14:15]
	v_lshlrev_b32_e32 v76, 16, v76
	v_or3_b32 v77, 0, v79, v76
	v_or3_b32 v76, v78, 0, 0
	v_lshrrev_b64 v[78:79], v150, s[12:13]
	v_lshlrev_b32_e32 v78, 16, v78
	v_or3_b32 v79, 0, v81, v78
	v_or3_b32 v78, v80, 0, 0
	global_store_dwordx2 v[126:127], v[78:79], off offset:-1024
	global_store_dwordx2 v[126:127], v[76:77], off offset:-512
	global_store_dwordx2 v[126:127], v[74:75], off
	global_store_dwordx2 v[126:127], v[72:73], off offset:512
	s_branch .LBB0_1001

; DI float softmax_step(f32x4 (&st)[4], float& m, float& lsum) {
;   float mx = fmaxf(fmaxf(fmaxf(st[0][0], st[0][1]), fmaxf(st[0][2], st[0][3])), fmaxf(fmaxf(st[1][0], st[1][1]), fmaxf(st[1][2], st[1][3])));
;   mx = fmaxf(mx, fmaxf(fmaxf(fmaxf(st[2][0], st[2][1]), fmaxf(st[2][2], st[2][3])), fmaxf(fmaxf(st[3][0], st[3][1]), fmaxf(st[3][2], st[3][3]))));
;   mx = fmaxf(mx, __shfl_xor(mx, 16)); mx = fmaxf(mx, __shfl_xor(mx, 32));
.LBB0_1079:
	v_readlane_b32 s16, v254, 55
	s_add_i32 s1, s15, -2
	v_readlane_b32 s18, v254, 57
	v_readlane_b32 s19, v254, 58
	v_cmp_le_i32_e32 vcc, s1, v107
	v_readlane_b32 s17, v254, 56
	v_lshl_add_u64 v[122:123], s[18:19], 0, v[112:113]
	s_and_saveexec_b64 s[12:13], vcc
	s_cbranch_execz .LBB0_1081
	v_add_co_u32_e32 v80, vcc, 0x1b900000, v122
	s_mov_b32 s16, 0xff800000
	s_nop 0
	v_addc_co_u32_e32 v81, vcc, 0, v123, vcc
	global_load_dwordx2 v[126:127], v[80:81], off
	v_add_co_u32_e32 v80, vcc, 0x1b902000, v122
	s_waitcnt vmcnt(0)
	v_lshrrev_b32_e32 v147, v132, v126
	v_addc_co_u32_e32 v81, vcc, 0, v123, vcc
	global_load_dwordx2 v[128:129], v[80:81], off
	ds_read_b128 v[80:83], v139
	ds_read_b128 v[84:87], v140
	s_waitcnt lgkmcnt(1)
	v_mfma_f32_16x16x32_f16 v[88:91], v[80:83], v[0:3], 0
	v_and_b32_e32 v130, 1, v147
	v_cmp_eq_u32_e32 vcc, 1, v130
	v_bfe_i32 v141, v147, 1, 1
	v_mfma_f32_16x16x32_f16 v[80:83], v[80:83], v[4:7], 0
	v_lshrrev_b32_e32 v126, v138, v126
	s_waitcnt lgkmcnt(0)
	v_mfma_f32_16x16x32_f16 v[142:145], v[84:87], v[8:11], v[88:91]
	v_mfma_f32_16x16x32_f16 v[154:157], v[84:87], v[12:15], v[80:83]
	s_nop 3
	ds_read_b128 v[80:83], v139 offset:2048
	ds_read_b128 v[84:87], v140 offset:2048
	s_waitcnt lgkmcnt(1)
	v_mfma_f32_16x16x32_f16 v[88:91], v[80:83], v[0:3], 0
	v_mfma_f32_16x16x32_f16 v[80:83], v[80:83], v[4:7], 0
	s_waitcnt lgkmcnt(0)
	v_mfma_f32_16x16x32_f16 v[100:103], v[84:87], v[8:11], v[88:91]
	v_mfma_f32_16x16x32_f16 v[96:99], v[84:87], v[12:15], v[80:83]
	s_nop 4
	ds_read_b128 v[80:83], v139 offset:4096
	ds_read_b128 v[88:91], v140 offset:4096
	s_waitcnt lgkmcnt(1)
	v_mfma_f32_16x16x32_f16 v[84:87], v[80:83], v[0:3], 0
	v_mfma_f32_16x16x32_f16 v[80:83], v[80:83], v[4:7], 0
	s_waitcnt lgkmcnt(0)
	v_mfma_f32_16x16x32_f16 v[84:87], v[88:91], v[8:11], v[84:87]
	v_mfma_f32_16x16x32_f16 v[80:83], v[88:91], v[12:15], v[80:83]
	ds_read_b128 v[88:91], v139 offset:6144
	ds_read_b128 v[92:95], v140 offset:6144
	s_waitcnt lgkmcnt(1)
	v_mfma_f32_16x16x32_f16 v[158:161], v[88:91], v[0:3], 0
	v_mfma_f32_16x16x32_f16 v[162:165], v[88:91], v[4:7], 0
	s_waitcnt lgkmcnt(0)
	v_mfma_f32_16x16x32_f16 v[88:91], v[92:95], v[8:11], v[158:161]
	s_nop 4
	v_cndmask_b32_e32 v159, v187, v142, vcc
	v_bfe_i32 v142, v147, 2, 1
	v_mfma_f32_16x16x32_f16 v[92:95], v[92:95], v[12:15], v[162:165]
	s_waitcnt vmcnt(0)
	v_lshrrev_b32_e32 v158, v132, v128
	v_and_b32_e32 v130, 1, v158
	v_cmp_eq_u32_e32 vcc, 1, v130
	v_lshrrev_b32_e32 v128, v138, v128
	s_nop 0
	v_cndmask_b32_e32 v130, v187, v154, vcc
	v_bfi_b32 v154, v141, v143, v187
	v_and_b32_e32 v141, 2, v158
	v_cmp_ne_u32_e32 vcc, 0, v141
	v_bfe_i32 v143, v147, 3, 1
	v_bfe_i32 v147, v126, 0, 1
	v_cndmask_b32_e32 v141, v187, v155, vcc
	v_bfi_b32 v144, v142, v144, v187
	v_and_b32_e32 v142, 4, v158
	v_cmp_ne_u32_e32 vcc, 0, v142
	s_nop 1
	v_cndmask_b32_e32 v142, v187, v156, vcc
	v_bfi_b32 v145, v143, v145, v187
	v_and_b32_e32 v143, 8, v158
	v_cmp_ne_u32_e32 vcc, 0, v143
	s_nop 1
	v_cndmask_b32_e32 v143, v187, v157, vcc
	v_bfi_b32 v100, v147, v100, v187
	v_and_b32_e32 v147, 1, v128
	v_cmp_eq_u32_e32 vcc, 1, v147
	s_nop 1
	v_cndmask_b32_e32 v147, v187, v96, vcc
	v_and_b32_e32 v96, 2, v126
	v_cmp_ne_u32_e32 vcc, 0, v96
	s_nop 1
	v_cndmask_b32_e32 v96, v187, v101, vcc
	v_bfe_i32 v101, v128, 1, 1
	v_bfi_b32 v97, v101, v97, v187
	v_and_b32_e32 v101, 4, v126
	v_cmp_ne_u32_e32 vcc, 0, v101
	s_nop 1
	v_cndmask_b32_e32 v101, v187, v102, vcc
	v_bfe_i32 v102, v128, 2, 1
	v_bfi_b32 v98, v102, v98, v187
	v_and_b32_e32 v102, 8, v126
	v_lshrrev_b32_e32 v126, v132, v129
	v_cmp_ne_u32_e32 vcc, 0, v102
	s_nop 1
	v_cndmask_b32_e32 v102, v187, v103, vcc
	v_and_b32_e32 v103, 8, v128
	v_cmp_ne_u32_e32 vcc, 0, v103
	s_nop 1
	v_cndmask_b32_e32 v103, v187, v99, vcc
	v_lshrrev_b32_e32 v99, v132, v127
	v_bfe_i32 v128, v99, 0, 1
	v_bfi_b32 v84, v128, v84, v187
	v_and_b32_e32 v128, 1, v126
	v_cmp_eq_u32_e32 vcc, 1, v128
	s_nop 1
	v_cndmask_b32_e32 v128, v187, v80, vcc
	v_and_b32_e32 v80, 2, v99
	v_cmp_ne_u32_e32 vcc, 0, v80
	s_nop 1
	v_cndmask_b32_e32 v80, v187, v85, vcc
	v_bfe_i32 v85, v126, 1, 1
	v_bfi_b32 v81, v85, v81, v187
	v_and_b32_e32 v85, 4, v99
	v_cmp_ne_u32_e32 vcc, 0, v85
	s_nop 1
	v_cndmask_b32_e32 v85, v187, v86, vcc
	v_bfe_i32 v86, v126, 2, 1
	v_bfi_b32 v155, v86, v82, v187
	v_bfe_i32 v86, v126, 3, 1
	v_and_b32_e32 v82, 8, v99
	v_cmp_ne_u32_e32 vcc, 0, v82
	s_nop 1
	v_cndmask_b32_e32 v82, v187, v87, vcc
	v_bfi_b32 v83, v86, v83, v187
	v_lshrrev_b32_e32 v86, v138, v127
	v_lshrrev_b32_e32 v87, v138, v129
	v_bfe_i32 v99, v86, 0, 1
	v_bfi_b32 v88, v99, v88, v187
	v_bfe_i32 v99, v87, 0, 1
	v_bfi_b32 v126, v99, v92, v187
	v_bfe_i32 v92, v86, 1, 1
	v_bfi_b32 v89, v92, v89, v187
	v_bfe_i32 v92, v87, 1, 1
	v_bfi_b32 v127, v92, v93, v187
	v_bfe_i32 v92, v86, 2, 1
	v_bfe_i32 v86, v86, 3, 1
	v_bfi_b32 v93, v92, v90, v187
	v_bfe_i32 v90, v87, 2, 1
	v_bfi_b32 v129, v90, v94, v187
	v_bfi_b32 v91, v86, v91, v187
	v_bfe_i32 v86, v87, 3, 1
	v_bfi_b32 v156, v86, v95, v187
	v_max_f32_e32 v86, v144, v145
	v_max_f32_e32 v87, v101, v102
	v_max_f32_e32 v90, v84, v80
	v_max_f32_e32 v92, v85, v82
	v_max_f32_e32 v94, v93, v91
	v_max3_f32 v94, v88, v89, v94
	v_max3_f32 v86, v159, v154, v86
	v_max3_f32 v87, v100, v96, v87
	v_max3_f32 v90, v90, v92, v94
	v_max3_f32 v86, v86, v87, v90
	ds_bpermute_b32 v87, v189, v86
	s_waitcnt lgkmcnt(0)
	v_max_f32_e32 v86, v86, v87
	ds_bpermute_b32 v87, v188, v86
	s_waitcnt lgkmcnt(0)
; DI float softmax_step(f32x4 (&st)[4], float& m, float& lsum) {
;   float mx = fmaxf(fmaxf(fmaxf(st[0][0], st[0][1]), fmaxf(st[0][2], st[0][3])), fmaxf(fmaxf(st[1][0], st[1][1]), fmaxf(st[1][2], st[1][3])));
;   mx = fmaxf(mx, fmaxf(fmaxf(fmaxf(st[2][0], st[2][1]), fmaxf(st[2][2], st[2][3])), fmaxf(fmaxf(st[3][0], st[3][1]), fmaxf(st[3][2], st[3][3]))));
;   mx = fmaxf(mx, __shfl_xor(mx, 16)); mx = fmaxf(mx, __shfl_xor(mx, 32));
;   const float mn = fmaxf(m, mx);
;   const float mu = mn == -INFINITY ? 0.f : mn;
;   const float alpha = __builtin_amdgcn_exp2f(m - mu);
;   float ps = 0.f;
; #pragma unroll
;   for (int kt = 0; kt < 4; ++kt)
; #pragma unroll
;     for (int j = 0; j < 4; ++j) { const float p = __builtin_amdgcn_exp2f(st[kt][j] - mu); st[kt][j] = p; ps += p; }
;   lsum = lsum * alpha + ps; m = mn;
;   return alpha;
; }
	v_max3_f32 v99, v131, v86, v87
	v_cmp_neq_f32_e32 vcc, s16, v99
	s_nop 1
	v_cndmask_b32_e32 v87, 0, v99, vcc
	v_sub_f32_e32 v86, v159, v87
	v_exp_f32_e32 v162, v86
	v_sub_f32_e32 v86, v154, v87
	v_exp_f32_e32 v164, v86
	v_sub_f32_e32 v86, v144, v87
	v_exp_f32_e32 v166, v86
	v_sub_f32_e32 v86, v145, v87
	v_sub_f32_e32 v80, v80, v87
	v_exp_f32_e32 v168, v86
	v_sub_f32_e32 v86, v100, v87
	v_exp_f32_e32 v94, v80
	v_sub_f32_e32 v80, v85, v87
	v_exp_f32_e32 v170, v86
	v_sub_f32_e32 v86, v96, v87
	v_exp_f32_e32 v92, v80
	v_sub_f32_e32 v80, v82, v87
	v_exp_f32_e32 v190, v86
	v_sub_f32_e32 v86, v101, v87
	v_exp_f32_e32 v90, v80
	v_sub_f32_e32 v80, v88, v87
	v_exp_f32_e32 v192, v86
	v_sub_f32_e32 v86, v102, v87
	v_exp_f32_e32 v88, v80
	v_sub_f32_e32 v80, v89, v87
	v_exp_f32_e32 v194, v86
	v_sub_f32_e32 v84, v84, v87
	v_exp_f32_e32 v86, v80
	v_sub_f32_e32 v80, v93, v87
	v_exp_f32_e32 v96, v84
	v_exp_f32_e32 v82, v80
	v_sub_f32_e32 v80, v91, v87
	v_sub_f32_e32 v84, v131, v87
	v_max_f32_e32 v85, v142, v143
	v_max_f32_e32 v87, v98, v103
	v_max_f32_e32 v89, v128, v81
	v_max_f32_e32 v91, v155, v83
	v_max_f32_e32 v93, v129, v156
	v_max3_f32 v93, v126, v127, v93
	v_max3_f32 v85, v130, v141, v85
	v_max3_f32 v87, v147, v97, v87
	v_max3_f32 v89, v89, v91, v93
	v_max3_f32 v85, v85, v87, v89
	ds_bpermute_b32 v87, v189, v85
	v_exp_f32_e32 v84, v84
	v_exp_f32_e32 v80, v80
	v_mov_b32_e32 v131, v99
	s_waitcnt lgkmcnt(0)
	v_max_f32_e32 v85, v85, v87
	ds_bpermute_b32 v87, v188, v85
	s_waitcnt lgkmcnt(0)
	v_max3_f32 v102, v146, v85, v87
	v_cmp_neq_f32_e32 vcc, s16, v102
	s_nop 1
	v_cndmask_b32_e32 v85, 0, v102, vcc
	v_sub_f32_e32 v87, v130, v85
	v_exp_f32_e32 v163, v87
	v_sub_f32_e32 v87, v141, v85
	v_exp_f32_e32 v165, v87
	v_sub_f32_e32 v87, v142, v85
	v_exp_f32_e32 v167, v87
	v_sub_f32_e32 v87, v143, v85
	v_exp_f32_e32 v169, v87
	v_sub_f32_e32 v87, v147, v85
	v_sub_f32_e32 v81, v81, v85
	v_exp_f32_e32 v171, v87
	v_sub_f32_e32 v87, v97, v85
	v_exp_f32_e32 v95, v81
	v_sub_f32_e32 v81, v155, v85
	v_exp_f32_e32 v191, v87
	v_sub_f32_e32 v87, v98, v85
	v_exp_f32_e32 v93, v81
	v_sub_f32_e32 v81, v83, v85
	v_exp_f32_e32 v193, v87
	v_sub_f32_e32 v87, v103, v85
	v_exp_f32_e32 v91, v81
	v_sub_f32_e32 v81, v126, v85
	v_exp_f32_e32 v195, v87
	v_sub_f32_e32 v87, v128, v85
	v_exp_f32_e32 v89, v81
	v_sub_f32_e32 v81, v127, v85
	v_exp_f32_e32 v97, v87
	v_exp_f32_e32 v87, v81
	v_sub_f32_e32 v81, v129, v85
	v_exp_f32_e32 v83, v81
	v_sub_f32_e32 v81, v156, v85
	v_sub_f32_e32 v85, v146, v85
	v_exp_f32_e32 v98, v85
	v_pk_mul_f32 v[156:157], v[70:71], v[84:85] op_sel_hi:[1,0]
	v_pk_mul_f32 v[154:155], v[68:69], v[84:85] op_sel_hi:[1,0]
	v_pk_mul_f32 v[128:129], v[62:63], v[84:85] op_sel_hi:[1,0]
	v_pk_mul_f32 v[142:143], v[56:57], v[98:99] op_sel_hi:[1,0]
	v_pk_mul_f32 v[70:71], v[50:51], v[98:99] op_sel_hi:[1,0]
	v_pk_mul_f32 v[68:69], v[48:49], v[98:99] op_sel_hi:[1,0]
	v_pk_mul_f32 v[50:51], v[74:75], v[84:85] op_sel_hi:[1,0]
	v_pk_mul_f32 v[48:49], v[72:73], v[84:85] op_sel_hi:[1,0]
	v_pk_add_f32 v[56:57], v[162:163], 0 op_sel_hi:[1,0]
	ds_read_b128 v[72:75], v139 offset:9216
	v_pk_add_f32 v[56:57], v[164:165], v[56:57]
	v_pk_mul_f32 v[126:127], v[60:61], v[84:85] op_sel_hi:[1,0]
	v_pk_add_f32 v[56:57], v[166:167], v[56:57]
	v_pk_mul_f32 v[144:145], v[58:59], v[98:99] op_sel_hi:[1,0]
	v_pk_add_f32 v[56:57], v[168:169], v[56:57]
	v_cvt_pk_f16_f32 v58, v170, v190
	v_pk_add_f32 v[56:57], v[170:171], v[56:57]
	v_cvt_pk_f16_f32 v59, v192, v194
	v_pk_add_f32 v[56:57], v[190:191], v[56:57]
	v_pk_mul_f32 v[160:161], v[66:67], v[98:99] op_sel_hi:[1,0]
	v_pk_add_f32 v[56:57], v[192:193], v[56:57]
	v_pk_mul_f32 v[158:159], v[64:65], v[98:99] op_sel_hi:[1,0]
	v_pk_add_f32 v[56:57], v[194:195], v[56:57]
	v_pk_mul_f32 v[66:67], v[54:55], v[84:85] op_sel_hi:[1,0]
	v_pk_add_f32 v[100:101], v[96:97], v[56:57]
	v_cvt_pk_f16_f32 v56, v162, v164
	v_cvt_pk_f16_f32 v57, v166, v168
	v_pk_mul_f32 v[64:65], v[52:53], v[84:85] op_sel_hi:[1,0]
	v_pk_mul_f32 v[54:55], v[78:79], v[98:99] op_sel_hi:[1,0]
	v_pk_mul_f32 v[52:53], v[76:77], v[98:99] op_sel_hi:[1,0]
	s_waitcnt lgkmcnt(0)
	v_mfma_f32_16x16x32_f16 v[76:79], v[72:75], v[56:59], v[126:129]
	v_cvt_pk_f16_f32 v60, v163, v165
	v_cvt_pk_f16_f32 v61, v167, v169
	v_cvt_pk_f16_f32 v62, v171, v191
	ds_read_b128 v[126:129], v139 offset:11264
	v_cvt_pk_f16_f32 v63, v193, v195
	v_exp_f32_e32 v81, v81
	v_cvt_pk_f16_f32 v190, v96, v94
	v_mfma_f32_16x16x32_f16 v[72:75], v[72:75], v[60:63], v[142:145]
	v_cvt_pk_f16_f32 v191, v92, v90
	v_cvt_pk_f16_f32 v192, v88, v86
	v_cvt_pk_f16_f32 v193, v82, v80
	s_waitcnt lgkmcnt(0)
	v_mfma_f32_16x16x32_f16 v[142:145], v[126:129], v[56:59], v[154:157]
	v_cvt_pk_f16_f32 v194, v97, v95
	v_cvt_pk_f16_f32 v195, v93, v91
	s_nop 0
	ds_read_b128 v[154:157], v139 offset:13312
	v_mfma_f32_16x16x32_f16 v[126:129], v[126:129], v[60:63], v[158:161]
	v_cvt_pk_f16_f32 v196, v89, v87
	v_cvt_pk_f16_f32 v197, v83, v81
	v_pk_add_f32 v[94:95], v[94:95], v[100:101]
	s_waitcnt lgkmcnt(0)
	v_mfma_f32_16x16x32_f16 v[158:161], v[154:157], v[56:59], v[64:67]
	s_nop 2
	ds_read_b128 v[64:67], v139 offset:15360
	v_pk_add_f32 v[92:93], v[92:93], v[94:95]
	v_mov_b32_e32 v85, v98
	s_waitcnt lgkmcnt(0)
	v_mfma_f32_16x16x32_f16 v[162:165], v[64:67], v[56:59], v[48:51]
	s_nop 2
	ds_read_b128 v[48:51], v140 offset:9216
	v_pk_add_f32 v[90:91], v[90:91], v[92:93]
	v_mov_b32_e32 v146, v102
	v_mfma_f32_16x16x32_f16 v[154:157], v[154:157], v[60:63], v[68:71]
	v_add_f32_e64 v88, v88, v90
	v_add_f32_e64 v89, v89, v91
	v_pk_add_f32 v[86:87], v[86:87], v[88:89]
	v_mfma_f32_16x16x32_f16 v[166:169], v[64:67], v[60:63], v[52:55]
	v_add_f32_e64 v82, v82, v86
	v_add_f32_e64 v83, v83, v87
	v_pk_add_f32 v[80:81], v[80:81], v[82:83]
	s_waitcnt lgkmcnt(0)
	v_mfma_f32_16x16x32_f16 v[60:63], v[48:51], v[190:193], v[76:79]
	v_fma_f32 v118, v118, v84, v80
	v_fma_f32 v119, v119, v85, v81
	v_mfma_f32_16x16x32_f16 v[56:59], v[48:51], v[194:197], v[72:75]
	ds_read_b128 v[48:51], v140 offset:11264
	ds_read_b128 v[76:79], v140 offset:15360
	s_waitcnt lgkmcnt(1)
	v_mfma_f32_16x16x32_f16 v[68:71], v[48:51], v[190:193], v[142:145]
	v_mfma_f32_16x16x32_f16 v[64:67], v[48:51], v[194:197], v[126:129]
	ds_read_b128 v[48:51], v140 offset:13312
	s_waitcnt lgkmcnt(0)
	v_mfma_f32_16x16x32_f16 v[52:55], v[48:51], v[190:193], v[158:161]
	v_mfma_f32_16x16x32_f16 v[48:51], v[48:51], v[194:197], v[154:157]
	v_mfma_f32_16x16x32_f16 v[72:75], v[76:79], v[190:193], v[162:165]
	v_mfma_f32_16x16x32_f16 v[76:79], v[76:79], v[194:197], v[166:169]

; DI float softmax_step(f32x4 (&st)[4], float& m, float& lsum) {
;   float mx = fmaxf(fmaxf(fmaxf(st[0][0], st[0][1]), fmaxf(st[0][2], st[0][3])), fmaxf(fmaxf(st[1][0], st[1][1]), fmaxf(st[1][2], st[1][3])));
;   mx = fmaxf(mx, fmaxf(fmaxf(fmaxf(st[2][0], st[2][1]), fmaxf(st[2][2], st[2][3])), fmaxf(fmaxf(st[3][0], st[3][1]), fmaxf(st[3][2], st[3][3]))));
;   mx = fmaxf(mx, __shfl_xor(mx, 16)); mx = fmaxf(mx, __shfl_xor(mx, 32));
.LBB0_1085:
	v_add_co_u32_e32 v80, vcc, 0x1b900000, v122
	s_mov_b32 s1, 0xff800000
	s_nop 0
	v_addc_co_u32_e32 v81, vcc, 0, v123, vcc
	global_load_dwordx2 v[128:129], v[80:81], off offset:8
	v_add_co_u32_e32 v80, vcc, 0x1b902000, v122
	s_nop 1
	v_addc_co_u32_e32 v81, vcc, 0, v123, vcc
	global_load_dwordx2 v[144:145], v[80:81], off offset:8
	ds_read_b128 v[80:83], v139 offset:18432
	ds_read_b128 v[84:87], v140 offset:18432
	s_waitcnt lgkmcnt(1)
	v_mfma_f32_16x16x32_f16 v[88:91], v[80:83], v[0:3], 0
	v_mfma_f32_16x16x32_f16 v[80:83], v[80:83], v[4:7], 0
	s_waitcnt lgkmcnt(0)
	v_mfma_f32_16x16x32_f16 v[88:91], v[84:87], v[8:11], v[88:91]
	v_mfma_f32_16x16x32_f16 v[80:83], v[84:87], v[12:15], v[80:83]
	ds_read_b128 v[84:87], v139 offset:20480
	ds_read_b128 v[92:95], v140 offset:20480
	s_waitcnt lgkmcnt(1)
	v_mfma_f32_16x16x32_f16 v[96:99], v[84:87], v[0:3], 0
	v_mfma_f32_16x16x32_f16 v[84:87], v[84:87], v[4:7], 0
	s_waitcnt lgkmcnt(0)
	v_mfma_f32_16x16x32_f16 v[96:99], v[92:95], v[8:11], v[96:99]
	v_mfma_f32_16x16x32_f16 v[84:87], v[92:95], v[12:15], v[84:87]
	ds_read_b128 v[92:95], v139 offset:22528
	ds_read_b128 v[100:103], v140 offset:22528
	s_waitcnt lgkmcnt(1)
	v_mfma_f32_16x16x32_f16 v[120:123], v[92:95], v[0:3], 0
	v_mfma_f32_16x16x32_f16 v[92:95], v[92:95], v[4:7], 0
	s_waitcnt lgkmcnt(0)
	v_mfma_f32_16x16x32_f16 v[120:123], v[100:103], v[8:11], v[120:123]
	v_mfma_f32_16x16x32_f16 v[92:95], v[100:103], v[12:15], v[92:95]
	ds_read_b128 v[100:103], v139 offset:24576
	ds_read_b128 v[124:127], v140 offset:24576
	s_waitcnt lgkmcnt(1)
	v_mfma_f32_16x16x32_f16 v[154:157], v[100:103], v[0:3], 0
	v_mfma_f32_16x16x32_f16 v[100:103], v[100:103], v[4:7], 0
	s_waitcnt lgkmcnt(0)
	v_mfma_f32_16x16x32_f16 v[154:157], v[124:127], v[8:11], v[154:157]
	v_mfma_f32_16x16x32_f16 v[100:103], v[124:127], v[12:15], v[100:103]
	s_waitcnt vmcnt(1)
	v_lshrrev_b32_e32 v124, v132, v128
	v_bfe_i32 v126, v124, 0, 1
	v_bfi_b32 v88, v126, v88, v187
	s_waitcnt vmcnt(0)
	v_lshrrev_b32_e32 v125, v132, v144
	v_bfe_i32 v126, v125, 0, 1
	v_bfi_b32 v80, v126, v80, v187
	v_bfe_i32 v126, v124, 1, 1
	v_bfi_b32 v89, v126, v89, v187
	v_bfe_i32 v126, v125, 1, 1
	v_bfi_b32 v81, v126, v81, v187
	v_bfe_i32 v126, v124, 2, 1
	v_bfe_i32 v124, v124, 3, 1
	v_bfi_b32 v90, v126, v90, v187
	v_bfe_i32 v126, v125, 2, 1
	v_bfi_b32 v82, v126, v82, v187
	v_bfi_b32 v91, v124, v91, v187
	v_bfe_i32 v124, v125, 3, 1
	v_lshrrev_b32_e32 v125, v138, v144
	v_bfi_b32 v83, v124, v83, v187
	v_lshrrev_b32_e32 v124, v138, v128
	v_bfe_i32 v126, v124, 0, 1
	v_bfi_b32 v96, v126, v96, v187
	v_bfe_i32 v126, v125, 0, 1
	v_bfi_b32 v127, v126, v84, v187
	v_bfe_i32 v84, v124, 1, 1
	v_bfi_b32 v97, v84, v97, v187
	v_bfe_i32 v84, v125, 1, 1
	v_bfi_b32 v147, v84, v85, v187
	v_bfe_i32 v84, v124, 2, 1
	v_bfi_b32 v85, v84, v98, v187
	v_bfe_i32 v84, v125, 2, 1
	v_bfi_b32 v98, v84, v86, v187
	v_bfe_i32 v84, v124, 3, 1
	v_bfi_b32 v99, v84, v99, v187
	v_bfe_i32 v84, v125, 3, 1
	v_lshrrev_b32_e32 v86, v132, v145
	v_bfi_b32 v125, v84, v87, v187
	v_lshrrev_b32_e32 v84, v132, v129
	v_and_b32_e32 v87, 1, v84
	v_cmp_eq_u32_e32 vcc, 1, v87
	s_nop 1
	v_cndmask_b32_e32 v87, v187, v120, vcc
	v_bfe_i32 v120, v86, 0, 1
	v_bfi_b32 v92, v120, v92, v187
	v_and_b32_e32 v120, 2, v84
	v_cmp_ne_u32_e32 vcc, 0, v120
	s_nop 1
	v_cndmask_b32_e32 v120, v187, v121, vcc
	v_bfe_i32 v121, v86, 1, 1
	v_bfi_b32 v93, v121, v93, v187
	v_and_b32_e32 v121, 4, v84
	v_bfe_i32 v84, v84, 3, 1
	v_cmp_ne_u32_e32 vcc, 0, v121
	s_nop 1
	v_cndmask_b32_e32 v121, v187, v122, vcc
	v_bfe_i32 v122, v86, 2, 1
	v_bfi_b32 v94, v122, v94, v187
	v_bfi_b32 v122, v84, v123, v187
	v_bfe_i32 v84, v86, 3, 1
	v_lshrrev_b32_e32 v86, v138, v145
	v_bfi_b32 v95, v84, v95, v187
	v_lshrrev_b32_e32 v84, v138, v129
	v_and_b32_e32 v123, 1, v84
	v_cmp_eq_u32_e32 vcc, 1, v123
	v_bfe_i32 v124, v86, 0, 1
	s_nop 0
	v_cndmask_b32_e32 v123, v187, v154, vcc
	v_bfi_b32 v129, v124, v100, v187
	v_bfe_i32 v124, v86, 1, 1
	v_and_b32_e32 v100, 2, v84
	v_cmp_ne_u32_e32 vcc, 0, v100
	s_nop 1
	v_cndmask_b32_e32 v100, v187, v155, vcc
	v_bfi_b32 v101, v124, v101, v187
	v_bfe_i32 v124, v84, 2, 1
	v_bfe_i32 v84, v84, 3, 1
	v_bfi_b32 v128, v124, v156, v187
	v_bfe_i32 v124, v86, 2, 1
	v_bfi_b32 v102, v124, v102, v187
	v_bfi_b32 v130, v84, v157, v187
	v_bfe_i32 v84, v86, 3, 1
	v_bfi_b32 v103, v84, v103, v187
	v_max_f32_e32 v84, v90, v91
	v_max_f32_e32 v86, v85, v99
	v_max_f32_e32 v124, v87, v120
	v_max_f32_e32 v126, v121, v122
	v_max_f32_e32 v144, v128, v130
	v_max3_f32 v144, v123, v100, v144
	v_max3_f32 v84, v88, v89, v84
	v_max3_f32 v86, v96, v97, v86
	v_max3_f32 v124, v124, v126, v144
	v_max3_f32 v84, v84, v86, v124
	ds_bpermute_b32 v86, v189, v84
	s_waitcnt lgkmcnt(0)
	v_max_f32_e32 v84, v84, v86
	ds_bpermute_b32 v86, v188, v84
	s_waitcnt lgkmcnt(0)
	v_max3_f32 v144, v131, v84, v86
	v_cmp_neq_f32_e32 vcc, s1, v144
	s_nop 1
	v_cndmask_b32_e32 v145, 0, v144, vcc
	v_sub_f32_e32 v84, v88, v145
	v_sub_f32_e32 v88, v90, v145
	v_exp_f32_e32 v162, v88
	v_sub_f32_e32 v88, v91, v145
	v_sub_f32_e32 v85, v85, v145
	v_exp_f32_e32 v164, v88
	v_sub_f32_e32 v88, v96, v145
	v_exp_f32_e32 v170, v85
	v_sub_f32_e32 v85, v99, v145
	v_exp_f32_e32 v166, v88
	v_sub_f32_e32 v88, v97, v145
	v_exp_f32_e32 v190, v85
	v_sub_f32_e32 v85, v87, v145
	v_exp_f32_e32 v168, v88
	v_exp_f32_e32 v88, v85
	v_sub_f32_e32 v85, v120, v145
	v_exp_f32_e32 v90, v85
	v_sub_f32_e32 v85, v121, v145
	v_exp_f32_e32 v120, v85
	v_sub_f32_e32 v85, v122, v145
	v_exp_f32_e32 v122, v85
	v_sub_f32_e32 v85, v123, v145
	v_exp_f32_e32 v124, v85
	v_sub_f32_e32 v85, v100, v145
	v_exp_f32_e32 v126, v85
	v_sub_f32_e32 v85, v128, v145
	v_exp_f32_e32 v128, v85
	v_sub_f32_e32 v85, v130, v145
	v_exp_f32_e32 v130, v85
	v_sub_f32_e32 v85, v131, v145
	v_exp_f32_e32 v100, v85
	v_sub_f32_e32 v86, v89, v145
	v_max_f32_e32 v85, v82, v83
	v_max_f32_e32 v87, v98, v125
	v_max_f32_e32 v89, v92, v93
	v_max_f32_e32 v91, v94, v95
	v_max_f32_e32 v96, v102, v103
	v_max3_f32 v96, v129, v101, v96
	v_max3_f32 v85, v80, v81, v85
	v_max3_f32 v87, v127, v147, v87
	v_max3_f32 v89, v89, v91, v96
	v_max3_f32 v85, v85, v87, v89
	ds_bpermute_b32 v87, v189, v85
	v_exp_f32_e32 v84, v84
	v_exp_f32_e32 v86, v86
	v_pk_mul_f32 v[70:71], v[70:71], v[100:101] op_sel_hi:[1,0]
	v_pk_mul_f32 v[68:69], v[68:69], v[100:101] op_sel_hi:[1,0]
	s_waitcnt lgkmcnt(0)
; DI void gload2(R2& r, const bf16_t* gsrc, size_t gp, int tid) { r.a = ld_chunk(gsrc, gp, tid); r.b = ld_chunk(gsrc, gp, tid + 256); }
; DI void sstoreK2(const R2& r, char* sdst, int tid) { st_chunk_k(sdst, tid, r.a); st_chunk_k(sdst, tid + 256, r.b); }
; DI void sstoreV2(const R2& r, char* sdst, int tid) { st_chunk_v(sdst, tid, r.a); st_chunk_v(sdst, tid + 256, r.b); }
; DI float softmax_step(f32x4 (&st)[4], float& m, float& lsum) {
;   float mx = fmaxf(fmaxf(fmaxf(st[0][0], st[0][1]), fmaxf(st[0][2], st[0][3])), fmaxf(fmaxf(st[1][0], st[1][1]), fmaxf(st[1][2], st[1][3])));
;   mx = fmaxf(mx, fmaxf(fmaxf(fmaxf(st[2][0], st[2][1]), fmaxf(st[2][2], st[2][3])), fmaxf(fmaxf(st[3][0], st[3][1]), fmaxf(st[3][2], st[3][3]))));
;   mx = fmaxf(mx, __shfl_xor(mx, 16)); mx = fmaxf(mx, __shfl_xor(mx, 32));
;   const float mn = fmaxf(m, mx);
;   const float mu = mn == -INFINITY ? 0.f : mn;
;   const float alpha = __builtin_amdgcn_exp2f(m - mu);
;   float ps = 0.f;
; #pragma unroll
;   for (int kt = 0; kt < 4; ++kt)
; #pragma unroll
;     for (int j = 0; j < 4; ++j) { const float p = __builtin_amdgcn_exp2f(st[kt][j] - mu); st[kt][j] = p; ps += p; }
;   lsum = lsum * alpha + ps; m = mn;
;   return alpha;
; }
; DI void attn_C2x(const Params& P, int b, int head, int qp, char* smem, bf16_t* ybase, size_t ypitch) {
;     ...
;   R2 rk0, rv0, rk1, rv1;
;   gload2(rk0, kbase, PW, tid); gload2(rv0, vbase, SEQ, tid);
;   gload2(rk1, kbase + (size_t)64 * PW, PW, tid); gload2(rv1, vbase + 64, SEQ, tid);
;   sstoreK2(rk0, smem, tid); sstoreV2(rv0, smem + 9216, tid);
;   __syncthreads();
;   for (int n = 0; n <= nlast; n += 2) {
;     if (n + 2 <= nlast) { gload2(rk0, kbase + (size_t)(n + 2) * 64 * PW, PW, tid); gload2(rv0, vbase + (n + 2) * 64, SEQ, tid); }
;     C2X_COMPUTE(n, smem)
;     sstoreK2(rk1, smem + STAGE, tid); sstoreV2(rv1, smem + STAGE + 9216, tid);
;     __syncthreads();
;     if (n + 3 <= nlast) { gload2(rk1, kbase + (size_t)(n + 3) * 64 * PW, PW, tid); gload2(rv1, vbase + (n + 3) * 64, SEQ, tid); }
;     C2X_COMPUTE(n + 1, smem + STAGE)
;     if (n + 2 <= nlast) { sstoreK2(rk0, smem, tid); sstoreV2(rv0, smem + 9216, tid); }
;     __syncthreads();
	v_max_f32_e32 v85, v85, v87
	ds_bpermute_b32 v87, v188, v85
	v_pk_mul_f32 v[156:157], v[54:55], v[100:101] op_sel_hi:[1,0]
	v_pk_mul_f32 v[154:155], v[52:53], v[100:101] op_sel_hi:[1,0]
	s_waitcnt lgkmcnt(0)
	v_max3_f32 v145, v146, v85, v87
	v_cmp_neq_f32_e32 vcc, s1, v145
	s_nop 1
	v_cndmask_b32_e32 v96, 0, v145, vcc
	v_sub_f32_e32 v80, v80, v96
	v_exp_f32_e32 v85, v80
	v_sub_f32_e32 v80, v81, v96
	v_exp_f32_e32 v87, v80
	v_sub_f32_e32 v80, v82, v96
	v_exp_f32_e32 v163, v80
	v_sub_f32_e32 v80, v83, v96
	v_exp_f32_e32 v165, v80
	v_sub_f32_e32 v80, v127, v96
	v_exp_f32_e32 v167, v80
	v_sub_f32_e32 v80, v147, v96
	v_exp_f32_e32 v169, v80
	v_sub_f32_e32 v80, v98, v96
	v_exp_f32_e32 v171, v80
	v_sub_f32_e32 v80, v125, v96
	v_exp_f32_e32 v191, v80
	v_sub_f32_e32 v80, v92, v96
	v_exp_f32_e32 v89, v80
	v_sub_f32_e32 v80, v93, v96
	v_exp_f32_e32 v91, v80
	v_sub_f32_e32 v80, v94, v96
	v_exp_f32_e32 v121, v80
	v_sub_f32_e32 v80, v95, v96
	v_exp_f32_e32 v123, v80
	v_sub_f32_e32 v80, v129, v96
	v_exp_f32_e32 v125, v80
	v_sub_f32_e32 v80, v101, v96
	v_exp_f32_e32 v127, v80
	v_sub_f32_e32 v80, v102, v96
	v_exp_f32_e32 v129, v80
	v_sub_f32_e32 v80, v103, v96
	v_exp_f32_e32 v131, v80
	v_sub_f32_e32 v80, v146, v96
	v_exp_f32_e32 v102, v80
	v_pk_mul_f32 v[82:83], v[62:63], v[100:101] op_sel_hi:[1,0]
	v_pk_mul_f32 v[80:81], v[60:61], v[100:101] op_sel_hi:[1,0]
	v_cvt_pk_f16_f32 v60, v84, v86
	v_pk_mul_f32 v[160:161], v[50:51], v[102:103] op_sel_hi:[1,0]
	v_pk_mul_f32 v[158:159], v[48:49], v[102:103] op_sel_hi:[1,0]
	v_pk_mul_f32 v[50:51], v[74:75], v[100:101] op_sel_hi:[1,0]
	v_pk_mul_f32 v[48:49], v[72:73], v[100:101] op_sel_hi:[1,0]
	ds_read_b128 v[72:75], v139 offset:29696
	v_pk_mul_f32 v[92:93], v[56:57], v[102:103] op_sel_hi:[1,0]
	v_pk_add_f32 v[56:57], v[84:85], 0 op_sel_hi:[1,0]
	v_pk_mul_f32 v[98:99], v[66:67], v[102:103] op_sel_hi:[1,0]
	v_pk_add_f32 v[56:57], v[86:87], v[56:57]
	v_pk_mul_f32 v[96:97], v[64:65], v[102:103] op_sel_hi:[1,0]
	v_pk_add_f32 v[56:57], v[162:163], v[56:57]
	v_cvt_pk_f16_f32 v61, v162, v164
	v_pk_add_f32 v[56:57], v[164:165], v[56:57]
	v_cvt_pk_f16_f32 v62, v166, v168
	v_pk_add_f32 v[56:57], v[166:167], v[56:57]
	v_cvt_pk_f16_f32 v63, v170, v190
	v_pk_add_f32 v[56:57], v[168:169], v[56:57]
	v_cvt_pk_f16_f32 v84, v85, v87
	v_pk_add_f32 v[56:57], v[170:171], v[56:57]
	v_cvt_pk_f16_f32 v85, v163, v165
	v_cvt_pk_f16_f32 v86, v167, v169
	v_cvt_pk_f16_f32 v87, v171, v191
	ds_read_b128 v[64:67], v139 offset:27648
	v_pk_add_f32 v[56:57], v[190:191], v[56:57]
	s_waitcnt lgkmcnt(1)
	v_mfma_f32_16x16x32_f16 v[68:71], v[72:75], v[60:63], v[68:71]
	v_add_f32_e64 v56, v88, v56
	v_add_f32_e64 v57, v89, v57
	v_pk_mul_f32 v[94:95], v[58:59], v[102:103] op_sel_hi:[1,0]
	v_pk_add_f32 v[56:57], v[90:91], v[56:57]
	v_mfma_f32_16x16x32_f16 v[72:75], v[72:75], v[84:87], v[96:99]
	v_add_f32_e64 v56, v120, v56
	v_add_f32_e64 v57, v121, v57
	v_pk_mul_f32 v[54:55], v[78:79], v[102:103] op_sel_hi:[1,0]
	v_pk_add_f32 v[56:57], v[122:123], v[56:57]
	ds_read_b128 v[96:99], v139 offset:33792
	v_pk_add_f32 v[56:57], v[124:125], v[56:57]
	v_pk_mul_f32 v[52:53], v[76:77], v[102:103] op_sel_hi:[1,0]
	v_pk_add_f32 v[56:57], v[126:127], v[56:57]
	v_mov_b32_e32 v101, v102
	v_pk_add_f32 v[56:57], v[128:129], v[56:57]
	v_mov_b32_e32 v146, v145
	v_pk_add_f32 v[102:103], v[130:131], v[56:57]
	s_waitcnt lgkmcnt(1)
	v_mfma_f32_16x16x32_f16 v[56:59], v[64:67], v[60:63], v[80:83]
	v_fma_f32 v118, v118, v100, v102
	v_fma_f32 v119, v119, v101, v103
	s_nop 0
	ds_read_b128 v[80:83], v139 offset:31744
	v_mfma_f32_16x16x32_f16 v[64:67], v[64:67], v[84:87], v[92:95]
	s_waitcnt lgkmcnt(1)
	v_mfma_f32_16x16x32_f16 v[92:95], v[96:99], v[60:63], v[48:51]
	s_nop 2
	ds_read_b128 v[48:51], v140 offset:27648
	s_waitcnt lgkmcnt(1)
	v_mfma_f32_16x16x32_f16 v[76:79], v[80:83], v[60:63], v[154:157]
	v_mfma_f32_16x16x32_f16 v[80:83], v[80:83], v[84:87], v[158:161]
	v_mfma_f32_16x16x32_f16 v[84:87], v[96:99], v[84:87], v[52:55]
	v_cvt_pk_f16_f32 v96, v88, v90
	v_cvt_pk_f16_f32 v97, v120, v122
	v_cvt_pk_f16_f32 v98, v124, v126
	v_cvt_pk_f16_f32 v99, v128, v130
	v_cvt_pk_f16_f32 v88, v89, v91
	v_cvt_pk_f16_f32 v89, v121, v123
	v_cvt_pk_f16_f32 v90, v125, v127
	v_cvt_pk_f16_f32 v91, v129, v131
	s_waitcnt lgkmcnt(0)
	v_mfma_f32_16x16x32_f16 v[60:63], v[48:51], v[96:99], v[56:59]
	v_mov_b32_e32 v131, v144
	v_mfma_f32_16x16x32_f16 v[56:59], v[48:51], v[88:91], v[64:67]
	ds_read_b128 v[48:51], v140 offset:29696
	s_waitcnt lgkmcnt(0)
	v_mfma_f32_16x16x32_f16 v[68:71], v[48:51], v[96:99], v[68:71]
	v_mfma_f32_16x16x32_f16 v[64:67], v[48:51], v[88:91], v[72:75]
	ds_read_b128 v[48:51], v140 offset:31744
	s_waitcnt lgkmcnt(0)
	v_mfma_f32_16x16x32_f16 v[52:55], v[48:51], v[96:99], v[76:79]
	s_nop 2
	ds_read_b128 v[76:79], v140 offset:33792
	v_mfma_f32_16x16x32_f16 v[48:51], v[48:51], v[88:91], v[80:83]
	s_waitcnt lgkmcnt(0)
	v_mfma_f32_16x16x32_f16 v[72:75], v[76:79], v[96:99], v[92:95]
	v_mfma_f32_16x16x32_f16 v[76:79], v[76:79], v[88:91], v[84:87]
	s_or_b64 exec, exec, s[12:13]
	s_andn2_b64 vcc, exec, s[10:11]
	s_cbranch_vccnz .LBB0_1076
